# v070 + prompt scan loop head aligned to 64 bytes
# baseline (speedup 1.0000x reference)
.LBB0_360:
	s_waitcnt vmcnt(1)
	v_mov_b64_e32 v[42:43], v[22:23]
	s_waitcnt vmcnt(0)
	v_mov_b64_e32 v[46:47], v[18:19]
	s_sub_i32 s24, 0x810, s4
	s_and_b32 s47, s27, 1
	v_mov_b64_e32 v[40:41], v[20:21]
	v_mov_b64_e32 v[44:45], v[16:17]
	s_min_i32 s24, s24, 32
	v_lshl_add_u32 v132, s47, 12, v236
	s_setprio 3
	s_cmpk_gt_i32 s4, 0x80f
	v_mov_b32_e32 v131, 0
	s_cbranch_scc1 .LBB0_371
	s_mul_i32 s47, s47, 0xb000
	s_add_i32 s28, s47, 0
	v_lshl_add_u32 v134, v192, 2, s28
	v_add_u32_e32 v72, 0xa000, v134
	v_add_u32_e32 v133, s28, v196
	ds_read2_b64 v[16:19], v72 offset1:16
	ds_read_b128 v[20:23], v133 offset:33024
	ds_read_b128 v[24:27], v133 offset:32768
	ds_read_b128 v[28:31], v133 offset:24832
	ds_read_b128 v[48:51], v133 offset:24576
	ds_read_b128 v[52:55], v133 offset:16640
	ds_read_b128 v[56:59], v133 offset:16384
	ds_read_b128 v[60:63], v133 offset:8448
	ds_read_b128 v[64:67], v133 offset:8192
	ds_read_b128 v[68:71], v133 offset:256
	ds_read_b128 v[112:115], v133
	ds_read2_b64 v[80:83], v72 offset0:32 offset1:48
	ds_read_b128 v[104:107], v133 offset:512
	ds_read_b128 v[84:87], v133 offset:768
	ds_read_b128 v[120:123], v133 offset:8704
	ds_read_b128 v[92:95], v133 offset:8960
	ds_read_b128 v[96:99], v133 offset:16896
	ds_read_b128 v[72:75], v133 offset:17152
	ds_read_b128 v[108:111], v133 offset:25088
	ds_read_b128 v[88:91], v133 offset:25344
	ds_read_b128 v[100:103], v133 offset:33280
	ds_read_b128 v[76:79], v133 offset:33536
	s_waitcnt lgkmcnt(13)
	v_pk_mul_f32 v[116:117], v[202:203], v[66:67]
	v_pk_mul_f32 v[66:67], v[206:207], v[66:67]
	v_pk_fma_f32 v[116:117], v[204:205], v[64:65], v[116:117]
	v_pk_fma_f32 v[64:65], v[208:209], v[64:65], v[66:67]
	v_add_f32_e32 v66, v116, v117
	v_add_f32_e32 v64, v64, v65
	s_waitcnt lgkmcnt(11)
	v_pk_mul_f32 v[116:117], v[206:207], v[114:115]
	v_add_f32_dpp v65, v66, v66 quad_perm:[1,0,3,2] row_mask:0xf bank_mask:0xf bound_ctrl:1
	v_add_f32_dpp v64, v64, v64 quad_perm:[1,0,3,2] row_mask:0xf bank_mask:0xf bound_ctrl:1
	v_pk_fma_f32 v[116:117], v[16:17], v[50:51], v[116:117] op_sel:[1,0,0]
	v_add_f32_dpp v65, v65, v65 quad_perm:[2,3,0,1] row_mask:0xf bank_mask:0xf bound_ctrl:1
	v_add_f32_dpp v64, v64, v64 quad_perm:[2,3,0,1] row_mask:0xf bank_mask:0xf bound_ctrl:1
	s_nop 0
	v_add_f32_dpp v118, v65, v65 row_ror:4 row_mask:0xf bank_mask:0xf bound_ctrl:1
	v_add_f32_dpp v66, v64, v64 row_ror:4 row_mask:0xf bank_mask:0xf bound_ctrl:1
	v_pk_mul_f32 v[64:65], v[208:209], v[112:113]
	v_pk_mul_f32 v[112:113], v[204:205], v[112:113]
	v_pk_fma_f32 v[64:65], v[16:17], v[48:49], v[64:65] op_sel:[1,0,0]
	v_add_f32_dpp v66, v66, v66 row_ror:8 row_mask:0xf bank_mask:0xf bound_ctrl:1
	v_pk_fma_f32 v[48:49], v[16:17], v[48:49], v[112:113] op_sel_hi:[0,1,1]
	v_add_f32_dpp v112, v118, v118 row_ror:8 row_mask:0xf bank_mask:0xf bound_ctrl:1
	v_pk_fma_f32 v[64:65], v[56:57], v[66:67], v[64:65] op_sel_hi:[1,0,1] neg_lo:[1,0,0] neg_hi:[1,0,0]
	v_pk_fma_f32 v[48:49], v[56:57], v[112:113], v[48:49] op_sel_hi:[1,0,1] neg_lo:[1,0,0] neg_hi:[1,0,0]
	v_pk_mul_f32 v[56:57], v[202:203], v[114:115]
	v_pk_fma_f32 v[66:67], v[58:59], v[66:67], v[116:117] op_sel_hi:[1,0,1] neg_lo:[1,0,0] neg_hi:[1,0,0]
	v_pk_fma_f32 v[16:17], v[16:17], v[50:51], v[56:57] op_sel_hi:[0,1,1]
	v_pk_fma_f32 v[16:17], v[58:59], v[112:113], v[16:17] op_sel_hi:[1,0,1] neg_lo:[1,0,0] neg_hi:[1,0,0]
	v_pk_mul_f32 v[116:117], v[26:27], v[66:67]
	v_pk_mul_f32 v[26:27], v[26:27], v[16:17]
	v_pk_fma_f32 v[116:117], v[24:25], v[64:65], v[116:117]
	v_pk_fma_f32 v[24:25], v[24:25], v[48:49], v[26:27]
	v_pk_mul_f32 v[26:27], v[62:63], v[66:67]
	v_add_f32_e32 v131, v24, v25
	v_pk_mul_f32 v[24:25], v[62:63], v[16:17]
	v_pk_fma_f32 v[26:27], v[60:61], v[64:65], v[26:27]
	v_pk_fma_f32 v[24:25], v[60:61], v[48:49], v[24:25]
	v_add_f32_e32 v51, v26, v27
	v_add_f32_e32 v50, v24, v25
	v_pk_mul_f32 v[24:25], v[68:69], v[48:49]
	v_pk_mul_f32 v[26:27], v[68:69], v[64:65]
	v_pk_fma_f32 v[24:25], v[18:19], v[28:29], v[24:25] op_sel_hi:[0,1,1]
	v_pk_mul_f32 v[16:17], v[70:71], v[16:17]
	v_pk_fma_f32 v[26:27], v[18:19], v[28:29], v[26:27] op_sel:[1,0,0]
	v_pk_mul_f32 v[28:29], v[70:71], v[66:67]
	v_pk_fma_f32 v[16:17], v[18:19], v[30:31], v[16:17] op_sel_hi:[0,1,1]
	v_pk_fma_f32 v[18:19], v[18:19], v[30:31], v[28:29] op_sel:[1,0,0]
	v_add_f32_dpp v28, v50, v50 quad_perm:[1,0,3,2] row_mask:0xf bank_mask:0xf bound_ctrl:1
	v_add_f32_dpp v29, v51, v51 quad_perm:[1,0,3,2] row_mask:0xf bank_mask:0xf bound_ctrl:1
	v_add_f32_e32 v130, v116, v117
	v_add_f32_dpp v28, v28, v28 quad_perm:[2,3,0,1] row_mask:0xf bank_mask:0xf bound_ctrl:1
	v_add_f32_dpp v29, v29, v29 quad_perm:[2,3,0,1] row_mask:0xf bank_mask:0xf bound_ctrl:1
	s_nop 0
	v_add_f32_dpp v28, v28, v28 row_ror:4 row_mask:0xf bank_mask:0xf bound_ctrl:1
	v_add_f32_dpp v29, v29, v29 row_ror:4 row_mask:0xf bank_mask:0xf bound_ctrl:1
	s_nop 0
	v_add_f32_dpp v28, v28, v28 row_ror:8 row_mask:0xf bank_mask:0xf bound_ctrl:1
	v_add_f32_dpp v30, v29, v29 row_ror:8 row_mask:0xf bank_mask:0xf bound_ctrl:1
	v_pk_fma_f32 v[114:115], v[54:55], v[28:29], v[16:17] op_sel_hi:[1,0,1] neg_lo:[1,0,0] neg_hi:[1,0,0]
	v_pk_fma_f32 v[112:113], v[54:55], v[30:31], v[18:19] op_sel_hi:[1,0,1] neg_lo:[1,0,0] neg_hi:[1,0,0]
	v_pk_fma_f32 v[118:119], v[52:53], v[28:29], v[24:25] op_sel_hi:[1,0,1] neg_lo:[1,0,0] neg_hi:[1,0,0]
	v_pk_fma_f32 v[116:117], v[52:53], v[30:31], v[26:27] op_sel_hi:[1,0,1] neg_lo:[1,0,0] neg_hi:[1,0,0]
	v_pk_mul_f32 v[16:17], v[22:23], v[114:115]
	v_pk_mul_f32 v[18:19], v[22:23], v[112:113]
	v_pk_fma_f32 v[16:17], v[20:21], v[118:119], v[16:17]
	v_pk_fma_f32 v[18:19], v[20:21], v[116:117], v[18:19]
	v_add_f32_e32 v135, v16, v17
	v_add_f32_e32 v136, v18, v19
	s_cmpk_lt_i32 s4, 0x80c
	s_cselect_b64 s[78:79], -1, 0
	s_and_b64 s[28:29], s[78:79], exec
	s_cselect_b32 s28, 4, 0
	v_lshl_add_u32 v16, s28, 8, v133
	v_lshl_add_u32 v17, s28, 7, v134
	s_or_b32 s28, s28, 1
	v_lshl_add_u32 v56, s28, 8, v133
	ds_read_b128 v[68:71], v16 offset:8192
	ds_read_b128 v[28:31], v16 offset:16384
	ds_read_b128 v[60:63], v16
	ds_read_b128 v[52:55], v16 offset:32768
	ds_read_b128 v[64:67], v16 offset:24576
	ds_read_b64 v[126:127], v17 offset:40960
	ds_read_b128 v[48:51], v56 offset:8192
	ds_read_b128 v[16:19], v56 offset:16384
	ds_read_b128 v[24:27], v56
	ds_read_b128 v[20:23], v56 offset:32768
	v_lshl_add_u32 v124, s28, 7, v134
	ds_read_b128 v[56:59], v56 offset:24576
	ds_read_b64 v[124:125], v124 offset:40960
	s_waitcnt lgkmcnt(14)
	v_pk_mul_f32 v[128:129], v[122:123], v[114:115]
	v_pk_mul_f32 v[122:123], v[122:123], v[112:113]
	v_pk_fma_f32 v[128:129], v[120:121], v[118:119], v[128:129]
	v_pk_fma_f32 v[120:121], v[120:121], v[116:117], v[122:123]
	v_add_f32_e32 v122, v128, v129
	v_cndmask_b32_e64 v128, v131, v130, s[6:7]
	v_cndmask_b32_e64 v129, v135, v136, s[6:7]
	v_cndmask_b32_e64 v130, v130, v131, s[6:7]
	v_cndmask_b32_e64 v131, v136, v135, s[6:7]
	v_add_f32_e32 v120, v120, v121
	v_add_f32_dpp v128, v128, v130 quad_perm:[1,0,3,2] row_mask:0xf bank_mask:0xf bound_ctrl:1
	v_add_f32_dpp v129, v129, v131 quad_perm:[1,0,3,2] row_mask:0xf bank_mask:0xf bound_ctrl:1
	v_add_f32_dpp v121, v122, v122 quad_perm:[1,0,3,2] row_mask:0xf bank_mask:0xf bound_ctrl:1
	v_add_f32_dpp v120, v120, v120 quad_perm:[1,0,3,2] row_mask:0xf bank_mask:0xf bound_ctrl:1
	v_cndmask_b32_e64 v130, v128, v129, s[8:9]
	v_cndmask_b32_e64 v128, v129, v128, s[8:9]
	v_add_f32_dpp v121, v121, v121 quad_perm:[2,3,0,1] row_mask:0xf bank_mask:0xf bound_ctrl:1
	v_add_f32_dpp v122, v120, v120 quad_perm:[2,3,0,1] row_mask:0xf bank_mask:0xf bound_ctrl:1
	v_add_f32_dpp v128, v130, v128 quad_perm:[2,3,0,1] row_mask:0xf bank_mask:0xf bound_ctrl:1
	v_add_f32_dpp v120, v121, v121 row_ror:4 row_mask:0xf bank_mask:0xf bound_ctrl:1
	v_add_f32_dpp v121, v122, v122 row_ror:4 row_mask:0xf bank_mask:0xf bound_ctrl:1
	v_mov_b32_e32 v122, v177
	v_mov_b32_e32 v123, v177
	v_add_f32_dpp v128, v128, v128 row_ror:4 row_mask:0xf bank_mask:0xf bound_ctrl:1
	v_mov_b32_e32 v129, v177
	v_mov_b32_dpp v122, v120 row_ror:8 row_mask:0xf bank_mask:0xf
	v_mov_b32_dpp v123, v121 row_ror:8 row_mask:0xf bank_mask:0xf
	v_mov_b32_dpp v129, v128 row_ror:8 row_mask:0xf bank_mask:0xf
	s_and_saveexec_b64 s[80:81], s[10:11]
	v_add3_u32 v130, v132, v197, v240
	v_add_f32_e32 v128, v128, v129
	ds_write_b32 v130, v128
	s_or_b64 exec, exec, s[80:81]
	v_pk_mul_f32 v[118:119], v[104:105], v[118:119]
	v_pk_mul_f32 v[114:115], v[106:107], v[114:115]
	v_pk_mul_f32 v[104:105], v[104:105], v[116:117]
	v_pk_mul_f32 v[106:107], v[106:107], v[112:113]
	v_pk_fma_f32 v[118:119], v[108:109], v[80:81], v[118:119] op_sel_hi:[1,0,1]
	v_pk_fma_f32 v[114:115], v[110:111], v[80:81], v[114:115] op_sel_hi:[1,0,1]
	v_pk_fma_f32 v[104:105], v[108:109], v[80:81], v[104:105] op_sel:[0,1,0]
	v_pk_fma_f32 v[80:81], v[110:111], v[80:81], v[106:107] op_sel:[0,1,0]
	v_add_f32_e32 v106, v120, v122
	v_add_f32_e32 v108, v121, v123
	v_pk_fma_f32 v[110:111], v[96:97], v[106:107], v[118:119] op_sel_hi:[1,0,1] neg_lo:[1,0,0] neg_hi:[1,0,0]
	v_pk_fma_f32 v[106:107], v[98:99], v[106:107], v[114:115] op_sel_hi:[1,0,1] neg_lo:[1,0,0] neg_hi:[1,0,0]
	v_pk_fma_f32 v[80:81], v[98:99], v[108:109], v[80:81] op_sel_hi:[1,0,1] neg_lo:[1,0,0] neg_hi:[1,0,0]
	v_pk_fma_f32 v[96:97], v[96:97], v[108:109], v[104:105] op_sel_hi:[1,0,1] neg_lo:[1,0,0] neg_hi:[1,0,0]
	s_waitcnt lgkmcnt(13)
	v_pk_mul_f32 v[98:99], v[102:103], v[106:107]
	v_pk_mul_f32 v[102:103], v[102:103], v[80:81]
	v_pk_fma_f32 v[98:99], v[100:101], v[110:111], v[98:99]
	v_pk_fma_f32 v[100:101], v[100:101], v[96:97], v[102:103]
	v_mov_b32_e32 v103, v98
	v_mov_b32_e32 v102, v100
	v_mov_b32_e32 v98, v101
	v_pk_add_f32 v[128:129], v[102:103], v[98:99]
	v_pk_mul_f32 v[98:99], v[94:95], v[106:107]
	v_pk_mul_f32 v[94:95], v[94:95], v[80:81]
	v_pk_fma_f32 v[98:99], v[92:93], v[110:111], v[98:99]
	v_pk_fma_f32 v[92:93], v[92:93], v[96:97], v[94:95]
	v_add_f32_e32 v98, v98, v99
	v_add_f32_e32 v99, v92, v93
	v_pk_mul_f32 v[92:93], v[84:85], v[110:111]
	v_pk_mul_f32 v[94:95], v[86:87], v[106:107]
	v_pk_mul_f32 v[84:85], v[84:85], v[96:97]
	v_pk_mul_f32 v[80:81], v[86:87], v[80:81]
	v_pk_fma_f32 v[92:93], v[88:89], v[82:83], v[92:93] op_sel_hi:[1,0,1]
	v_pk_fma_f32 v[94:95], v[90:91], v[82:83], v[94:95] op_sel_hi:[1,0,1]
	v_pk_fma_f32 v[84:85], v[88:89], v[82:83], v[84:85] op_sel:[0,1,0]
	v_pk_fma_f32 v[80:81], v[90:91], v[82:83], v[80:81] op_sel:[0,1,0]
	v_add_f32_dpp v82, v98, v98 quad_perm:[1,0,3,2] row_mask:0xf bank_mask:0xf bound_ctrl:1
	v_add_f32_dpp v83, v99, v99 quad_perm:[1,0,3,2] row_mask:0xf bank_mask:0xf bound_ctrl:1
	s_nop 0
	v_add_f32_dpp v82, v82, v82 quad_perm:[2,3,0,1] row_mask:0xf bank_mask:0xf bound_ctrl:1
	v_add_f32_dpp v83, v83, v83 quad_perm:[2,3,0,1] row_mask:0xf bank_mask:0xf bound_ctrl:1
	s_nop 0
	v_add_f32_dpp v82, v82, v82 row_ror:4 row_mask:0xf bank_mask:0xf bound_ctrl:1
	v_add_f32_dpp v83, v83, v83 row_ror:4 row_mask:0xf bank_mask:0xf bound_ctrl:1
	s_nop 0
	v_add_f32_dpp v82, v82, v82 row_ror:8 row_mask:0xf bank_mask:0xf bound_ctrl:1
	v_add_f32_dpp v86, v83, v83 row_ror:8 row_mask:0xf bank_mask:0xf bound_ctrl:1
	v_pk_fma_f32 v[90:91], v[74:75], v[82:83], v[94:95] op_sel_hi:[1,0,1] neg_lo:[1,0,0] neg_hi:[1,0,0]
	v_pk_fma_f32 v[94:95], v[74:75], v[86:87], v[80:81] op_sel_hi:[1,0,1] neg_lo:[1,0,0] neg_hi:[1,0,0]
	v_pk_fma_f32 v[88:89], v[72:73], v[82:83], v[92:93] op_sel_hi:[1,0,1] neg_lo:[1,0,0] neg_hi:[1,0,0]
	v_pk_fma_f32 v[92:93], v[72:73], v[86:87], v[84:85] op_sel_hi:[1,0,1] neg_lo:[1,0,0] neg_hi:[1,0,0]
	s_waitcnt lgkmcnt(12)
	v_pk_mul_f32 v[72:73], v[78:79], v[90:91]
	v_pk_mul_f32 v[74:75], v[78:79], v[94:95]
	v_pk_fma_f32 v[72:73], v[76:77], v[88:89], v[72:73]
	v_pk_fma_f32 v[74:75], v[76:77], v[92:93], v[74:75]
	v_mov_b32_e32 v77, v72
	v_mov_b32_e32 v76, v74
	v_mov_b32_e32 v72, v75
	v_pk_add_f32 v[130:131], v[76:77], v[72:73]
	s_andn2_b64 vcc, exec, s[78:79]
	s_cbranch_vccnz .LBB0_372
	v_cndmask_b32_e64 v72, 0, 1, s[72:73]
	s_mov_b32 s28, 0xb000
	v_lshl_or_b32 v135, v72, 12, v241
	v_add_u32_e32 v135, 0x16100, v135
	v_mul_lo_u32 v72, v72, s28
	v_add_u32_e32 v136, v242, v72
	v_or_b32_e32 v137, v243, v72
	s_mov_b32 s47, 4
	.p2alignl 6, 3212836864
